# grid barrier: followers poll the single TOPGEN release word instead of per-XCD XGEN (on top of leader-post-before-inv)
# speedup vs baseline: 1.0008x; 1.0008x over previous
.LBB0_244:
	s_or_b64 exec, exec, s[8:9]
	v_cvt_f32_u32_e32 v4, v2
	s_waitcnt vmcnt(0)
	v_readfirstlane_b32 s6, v3
	v_sub_u32_e32 v3, 0, v2
	v_rcp_iflag_f32_e32 v4, v4
	v_add_u32_e32 v5, s6, v1
	v_mul_f32_e32 v4, 0x4f7ffffe, v4
	v_cvt_u32_f32_e32 v4, v4
	v_mul_lo_u32 v1, v3, v4
	v_mul_hi_u32 v1, v4, v1
	v_add_u32_e32 v1, v4, v1
	v_mul_hi_u32 v1, v5, v1
	v_mul_lo_u32 v3, v1, v2
	v_sub_u32_e32 v3, v5, v3
	v_add_u32_e32 v4, 1, v1
	v_cmp_ge_u32_e32 vcc, v3, v2
	s_nop 1
	v_cndmask_b32_e32 v1, v1, v4, vcc
	v_sub_u32_e32 v4, v3, v2
	v_cndmask_b32_e32 v3, v3, v4, vcc
	v_add_u32_e32 v4, 1, v1
	v_cmp_ge_u32_e32 vcc, v3, v2
	v_add_u32_e32 v3, 1, v5
	s_nop 0
	v_cndmask_b32_e32 v1, v1, v4, vcc
	v_mul_lo_u32 v4, v2, v1
	v_add_u32_e32 v2, v4, v2
	v_cmp_ne_u32_e32 vcc, v3, v2
	s_and_saveexec_b64 s[6:7], vcc
	s_xor_b64 s[6:7], exec, s[6:7]
	s_cbranch_execz .LBB0_258
	s_waitcnt lgkmcnt(0)
	s_add_u32 s16, s82, 0x983500
	s_addc_u32 s17, s83, 0
	v_mov_b32_e32 v0, 0
	global_load_dword v0, v0, s[16:17] sc1
	s_waitcnt vmcnt(0)
	v_cmp_eq_u32_e32 vcc, v0, v1
	s_and_saveexec_b64 s[8:9], vcc
	s_cbranch_execz .LBB0_257
	s_add_u32 s10, s82, 0x980200
	s_addc_u32 s11, s83, 0
	s_mov_b32 s28, 1
	s_mov_b64 s[18:19], 0
	v_mov_b32_e32 v0, 0
	s_branch .LBB0_248

.LBB0_385:
	s_or_b64 exec, exec, s[6:7]
	v_cvt_f32_u32_e32 v4, v2
	s_waitcnt vmcnt(0)
	v_readfirstlane_b32 s4, v3
	v_sub_u32_e32 v3, 0, v2
	v_rcp_iflag_f32_e32 v4, v4
	v_add_u32_e32 v5, s4, v1
	v_mul_f32_e32 v4, 0x4f7ffffe, v4
	v_cvt_u32_f32_e32 v4, v4
	v_mul_lo_u32 v1, v3, v4
	v_mul_hi_u32 v1, v4, v1
	v_add_u32_e32 v1, v4, v1
	v_mul_hi_u32 v1, v5, v1
	v_mul_lo_u32 v3, v1, v2
	v_sub_u32_e32 v3, v5, v3
	v_add_u32_e32 v4, 1, v1
	v_cmp_ge_u32_e32 vcc, v3, v2
	s_nop 1
	v_cndmask_b32_e32 v1, v1, v4, vcc
	v_sub_u32_e32 v4, v3, v2
	v_cndmask_b32_e32 v3, v3, v4, vcc
	v_add_u32_e32 v4, 1, v1
	v_cmp_ge_u32_e32 vcc, v3, v2
	v_add_u32_e32 v3, 1, v5
	s_nop 0
	v_cndmask_b32_e32 v1, v1, v4, vcc
	v_mul_lo_u32 v4, v2, v1
	v_add_u32_e32 v2, v4, v2
	v_cmp_ne_u32_e32 vcc, v3, v2
	s_and_saveexec_b64 s[4:5], vcc
	s_xor_b64 s[4:5], exec, s[4:5]
	s_cbranch_execz .LBB0_399
	s_waitcnt lgkmcnt(0)
	s_add_u32 s10, s82, 0x983500
	s_addc_u32 s11, s83, 0
	v_mov_b32_e32 v0, 0
	global_load_dword v0, v0, s[10:11] sc1
	s_waitcnt vmcnt(0)
	v_cmp_eq_u32_e32 vcc, v0, v1
	s_and_saveexec_b64 s[6:7], vcc
	s_cbranch_execz .LBB0_398
	s_add_u32 s8, s82, 0x980200
	s_addc_u32 s9, s83, 0
	s_mov_b32 s26, 1
	s_mov_b64 s[16:17], 0
	v_mov_b32_e32 v0, 0
	s_branch .LBB0_389

.LBB0_466:
	s_or_b64 exec, exec, s[8:9]
	v_cvt_f32_u32_e32 v4, v2
	s_waitcnt vmcnt(0)
	v_readfirstlane_b32 s6, v3
	v_sub_u32_e32 v3, 0, v2
	v_rcp_iflag_f32_e32 v4, v4
	v_add_u32_e32 v5, s6, v1
	v_mul_f32_e32 v4, 0x4f7ffffe, v4
	v_cvt_u32_f32_e32 v4, v4
	v_mul_lo_u32 v1, v3, v4
	v_mul_hi_u32 v1, v4, v1
	v_add_u32_e32 v1, v4, v1
	v_mul_hi_u32 v1, v5, v1
	v_mul_lo_u32 v3, v1, v2
	v_sub_u32_e32 v3, v5, v3
	v_add_u32_e32 v4, 1, v1
	v_cmp_ge_u32_e32 vcc, v3, v2
	s_nop 1
	v_cndmask_b32_e32 v1, v1, v4, vcc
	v_sub_u32_e32 v4, v3, v2
	v_cndmask_b32_e32 v3, v3, v4, vcc
	v_add_u32_e32 v4, 1, v1
	v_cmp_ge_u32_e32 vcc, v3, v2
	v_add_u32_e32 v3, 1, v5
	s_nop 0
	v_cndmask_b32_e32 v1, v1, v4, vcc
	v_mul_lo_u32 v4, v2, v1
	v_add_u32_e32 v2, v4, v2
	v_cmp_ne_u32_e32 vcc, v3, v2
	s_and_saveexec_b64 s[6:7], vcc
	s_xor_b64 s[6:7], exec, s[6:7]
	s_cbranch_execz .LBB0_480
	s_waitcnt lgkmcnt(0)
	s_add_u32 s18, s82, 0x983500
	s_addc_u32 s19, s83, 0
	v_mov_b32_e32 v0, 0
	global_load_dword v0, v0, s[18:19] sc1
	s_waitcnt vmcnt(0)
	v_cmp_eq_u32_e32 vcc, v0, v1
	s_and_saveexec_b64 s[8:9], vcc
	s_cbranch_execz .LBB0_479
	s_add_u32 s10, s82, 0x980200
	s_addc_u32 s11, s83, 0
	s_mov_b32 s30, 1
	s_mov_b64 s[20:21], 0
	v_mov_b32_e32 v0, 0
	s_branch .LBB0_470

.LBB0_633:
	s_or_b64 exec, exec, s[6:7]
	v_cvt_f32_u32_e32 v4, v2
	s_waitcnt vmcnt(0)
	v_readfirstlane_b32 s4, v3
	v_sub_u32_e32 v3, 0, v2
	v_rcp_iflag_f32_e32 v4, v4
	v_add_u32_e32 v5, s4, v1
	v_mul_f32_e32 v4, 0x4f7ffffe, v4
	v_cvt_u32_f32_e32 v4, v4
	v_mul_lo_u32 v1, v3, v4
	v_mul_hi_u32 v1, v4, v1
	v_add_u32_e32 v1, v4, v1
	v_mul_hi_u32 v1, v5, v1
	v_mul_lo_u32 v3, v1, v2
	v_sub_u32_e32 v3, v5, v3
	v_add_u32_e32 v4, 1, v1
	v_cmp_ge_u32_e32 vcc, v3, v2
	s_nop 1
	v_cndmask_b32_e32 v1, v1, v4, vcc
	v_sub_u32_e32 v4, v3, v2
	v_cndmask_b32_e32 v3, v3, v4, vcc
	v_add_u32_e32 v4, 1, v1
	v_cmp_ge_u32_e32 vcc, v3, v2
	v_add_u32_e32 v3, 1, v5
	s_nop 0
	v_cndmask_b32_e32 v1, v1, v4, vcc
	v_mul_lo_u32 v4, v2, v1
	v_add_u32_e32 v2, v4, v2
	v_cmp_ne_u32_e32 vcc, v3, v2
	s_and_saveexec_b64 s[4:5], vcc
	s_xor_b64 s[4:5], exec, s[4:5]
	s_cbranch_execz .LBB0_647
	s_waitcnt lgkmcnt(0)
	s_add_u32 s10, s82, 0x983500
	s_addc_u32 s11, s83, 0
	v_mov_b32_e32 v0, 0
	global_load_dword v0, v0, s[10:11] sc1
	s_waitcnt vmcnt(0)
	v_cmp_eq_u32_e32 vcc, v0, v1
	s_and_saveexec_b64 s[6:7], vcc
	s_cbranch_execz .LBB0_646
	s_add_u32 s8, s82, 0x980200
	s_addc_u32 s9, s83, 0
	s_mov_b32 s22, 1
	s_mov_b64 s[12:13], 0
	v_mov_b32_e32 v0, 0
	s_branch .LBB0_637

.LBB0_814:
	s_or_b64 exec, exec, s[6:7]
	v_cvt_f32_u32_e32 v4, v2
	s_waitcnt vmcnt(0)
	v_readfirstlane_b32 s4, v3
	v_sub_u32_e32 v3, 0, v2
	v_rcp_iflag_f32_e32 v4, v4
	v_add_u32_e32 v5, s4, v1
	v_mul_f32_e32 v4, 0x4f7ffffe, v4
	v_cvt_u32_f32_e32 v4, v4
	v_mul_lo_u32 v1, v3, v4
	v_mul_hi_u32 v1, v4, v1
	v_add_u32_e32 v1, v4, v1
	v_mul_hi_u32 v1, v5, v1
	v_mul_lo_u32 v3, v1, v2
	v_sub_u32_e32 v3, v5, v3
	v_add_u32_e32 v4, 1, v1
	v_cmp_ge_u32_e32 vcc, v3, v2
	s_nop 1
	v_cndmask_b32_e32 v1, v1, v4, vcc
	v_sub_u32_e32 v4, v3, v2
	v_cndmask_b32_e32 v3, v3, v4, vcc
	v_add_u32_e32 v4, 1, v1
	v_cmp_ge_u32_e32 vcc, v3, v2
	v_add_u32_e32 v3, 1, v5
	s_nop 0
	v_cndmask_b32_e32 v1, v1, v4, vcc
	v_mul_lo_u32 v4, v2, v1
	v_add_u32_e32 v2, v4, v2
	v_cmp_ne_u32_e32 vcc, v3, v2
	s_and_saveexec_b64 s[4:5], vcc
	s_xor_b64 s[4:5], exec, s[4:5]
	s_cbranch_execz .LBB0_828
	s_waitcnt lgkmcnt(0)
	s_add_u32 s10, s70, 0x983500
	s_addc_u32 s11, s71, 0
	v_mov_b32_e32 v0, 0
	global_load_dword v0, v0, s[10:11] sc1
	s_waitcnt vmcnt(0)
	v_cmp_eq_u32_e32 vcc, v0, v1
	s_and_saveexec_b64 s[6:7], vcc
	s_cbranch_execz .LBB0_827
	s_add_u32 s8, s70, 0x980200
	s_addc_u32 s9, s71, 0
	s_mov_b32 s22, 1
	s_mov_b64 s[12:13], 0
	v_mov_b32_e32 v0, 0
	s_branch .LBB0_818

.LBB0_954:
	s_or_b64 exec, exec, s[8:9]
	v_cvt_f32_u32_e32 v4, v2
	s_waitcnt vmcnt(0)
	v_readfirstlane_b32 s6, v3
	v_sub_u32_e32 v3, 0, v2
	v_rcp_iflag_f32_e32 v4, v4
	v_add_u32_e32 v5, s6, v1
	v_mul_f32_e32 v4, 0x4f7ffffe, v4
	v_cvt_u32_f32_e32 v4, v4
	v_mul_lo_u32 v1, v3, v4
	v_mul_hi_u32 v1, v4, v1
	v_add_u32_e32 v1, v4, v1
	v_mul_hi_u32 v1, v5, v1
	v_mul_lo_u32 v3, v1, v2
	v_sub_u32_e32 v3, v5, v3
	v_add_u32_e32 v4, 1, v1
	v_cmp_ge_u32_e32 vcc, v3, v2
	s_nop 1
	v_cndmask_b32_e32 v1, v1, v4, vcc
	v_sub_u32_e32 v4, v3, v2
	v_cndmask_b32_e32 v3, v3, v4, vcc
	v_add_u32_e32 v4, 1, v1
	v_cmp_ge_u32_e32 vcc, v3, v2
	v_add_u32_e32 v3, 1, v5
	s_nop 0
	v_cndmask_b32_e32 v1, v1, v4, vcc
	v_mul_lo_u32 v4, v2, v1
	v_add_u32_e32 v2, v4, v2
	v_cmp_ne_u32_e32 vcc, v3, v2
	s_and_saveexec_b64 s[6:7], vcc
	s_xor_b64 s[6:7], exec, s[6:7]
	s_cbranch_execz .LBB0_968
	s_waitcnt lgkmcnt(0)
	s_add_u32 s12, s70, 0x983500
	s_addc_u32 s13, s71, 0
	v_mov_b32_e32 v0, 0
	global_load_dword v0, v0, s[12:13] sc1
	s_waitcnt vmcnt(0)
	v_cmp_eq_u32_e32 vcc, v0, v1
	s_and_saveexec_b64 s[8:9], vcc
	s_cbranch_execz .LBB0_967
	s_add_u32 s10, s70, 0x980200
	s_addc_u32 s11, s71, 0
	s_mov_b32 s24, 1
	s_mov_b64 s[14:15], 0
	v_mov_b32_e32 v0, 0
	s_branch .LBB0_958
